# GEMM K-loops: loop counter/pointer updates and exit compare moved from behind the loop-back barrier into the last MFMA block's idle issue slots (7.11, scalar part)
# speedup vs baseline: 1.0107x; 1.0107x over previous
; #define PG8_STAGE(bufoff, gbase, voff) do { _Pragma("unroll") for (int _i = 0; _i < 2; ++_i) \
;         __builtin_amdgcn_global_load_lds((const unsigned*)((const char*)(gbase) + (voff)[_i]), (PG8_LAS unsigned*)(lds + (bufoff) + ldsw + _i * 8192), 16, 0, 0); } while (0)
; #define PG8_LDA(dst, b, h) do { _Pragma("unroll") for (int m = 0; m < 4; ++m) _Pragma("unroll") for (int k = 0; k < 2; ++k) dst[m][k] = *(const PG8_LAS bf16x8*)(lds + PG8_SA(b, h) + aoff + m * 2048 + k * 1024); } while (0)
; #define PG8_LDB(dst, b, h) do { _Pragma("unroll") for (int n = 0; n < 2; ++n) _Pragma("unroll") for (int k = 0; k < 2; ++k) dst[n][k] = *(const PG8_LAS bf16x8*)(lds + PG8_SB(b, h) + boff + n * 2048 + k * 1024); } while (0)
; #define PG8_MMA(ai, bj, At, Bt) do { __builtin_amdgcn_s_setprio(1); _Pragma("unroll") for (int m = 0; m < 4; ++m) _Pragma("unroll") for (int n = 0; n < 2; ++n) _Pragma("unroll") for (int k = 0; k < 2; ++k) \
;         acc[ai][bj][m][n] = __builtin_amdgcn_mfma_f32_16x16x32_bf16(Bt[n][k], At[m][k], acc[ai][bj][m][n], 0, 0, 0); __builtin_amdgcn_s_setprio(0); } while (0)
; #define PG8_WAIT_V(n) asm volatile("s_waitcnt vmcnt(" #n ")" ::: "memory")
; template <class Epi, class Sched, bool ALIGN_EPI = false, bool SP2 = false, bool UNIFORM_NT = false>
; __device__ __forceinline__ void gemm_phase(PG8_LAS unsigned char* lds, const Gemm g, const Sched& S, const Epi& E, int tid_in) {
;     ...
;         for (int t = 0; t < nt; t += 2) {
;             const bool last = (t == nt - 2);
;             const char* a1 = cA + (size_t)(t + 1) * kstep;
;             const char* a2 = last ? nA : cA + (size_t)(t + 2) * kstep; const char* b2 = last ? nB : cB + (size_t)(t + 2) * kstep;
;             const char* a3 = a2 + kstep; const char* b3 = b2 + kstep;
;             if (last && has_next) S.a_ready(nxt);
;             if constexpr (SP2) {
;             PG8_LDB(B0, 0, 0); PG8_LDB(B1, 0, 1); PG8_SCHED; PG8_LDA(At, 0, 0); PG8_STAGE(PG8_SA(1, 1), a1 + hstepA, voffA);
;             PG8_WAIT_V(8); PG8_WAIT_L(0); PG8_BAR; PG8_MMA(0, 0, At, B0); PG8_MMA(0, 1, At, B1); PG8_BAR; PG8_SCHED;
;             PG8_LDA(At, 0, 1); PG8_STAGE(PG8_SB(0, 0), b2, voffB); PG8_STAGE(PG8_SB(0, 1), b2 + hstepB, voffB); PG8_STAGE(PG8_SA(0, 0), a2, voffA);
;             PG8_WAIT_V(8); PG8_WAIT_L(0); PG8_BAR; PG8_MMA(1, 0, At, B0); PG8_MMA(1, 1, At, B1); PG8_BAR; PG8_SCHED;
.LBB0_54:
	s_add_u32 s47, s54, 0xfffc0080
	s_addc_u32 s48, s55, -1
	s_add_i32 s49, 0, 0x10000
	s_cmp_eq_u32 s46, 12
	s_cselect_b32 s59, s12, s48
	s_cselect_b32 s58, s13, s47
	v_add_u32_e32 v140, s49, v143
	s_cselect_b32 s57, s31, s45
	s_cselect_b32 s56, s35, s43
	s_add_i32 s47, 0, 0x14000
	ds_read_b128 v[146:149], v140
	ds_read_b128 v[150:153], v140 offset:1024
	ds_read_b128 v[154:157], v140 offset:2048
	ds_read_b128 v[158:161], v140 offset:3072
	v_add_u32_e32 v140, s47, v143
	ds_read_b128 v[162:165], v140
	ds_read_b128 v[166:169], v140 offset:1024
	ds_read_b128 v[170:173], v140 offset:2048
	ds_read_b128 v[174:177], v140 offset:3072
	v_lshl_add_u64 v[140:141], s[54:55], 0, v[136:137]
	s_add_i32 m0, s7, 0xc000
	ds_read_b128 v[178:181], v145
	ds_read_b128 v[182:185], v145 offset:1024
	ds_read_b128 v[186:189], v145 offset:2048
	ds_read_b128 v[190:193], v145 offset:3072
	ds_read_b128 v[194:197], v145 offset:4096
	ds_read_b128 v[198:201], v145 offset:5120
	ds_read_b128 v[202:205], v145 offset:6144
	ds_read_b128 v[206:209], v145 offset:7168
	global_load_lds_dwordx4 v[140:141], off
	v_lshl_add_u64 v[140:141], s[54:55], 0, v[138:139]
	s_add_i32 m0, s7, 0xe000
	s_nop 0
	global_load_lds_dwordx4 v[140:141], off
	s_waitcnt vmcnt(8)
	s_waitcnt lgkmcnt(0)
	s_barrier
	s_setprio 1
	s_waitcnt lgkmcnt(0)
	v_mfma_f32_16x16x32_bf16 v[126:129], v[146:149], v[178:181], v[126:129]
	v_mfma_f32_16x16x32_bf16 v[122:125], v[154:157], v[178:181], v[122:125]
	v_mfma_f32_16x16x32_bf16 v[110:113], v[146:149], v[186:189], v[110:113]
	v_mfma_f32_16x16x32_bf16 v[106:109], v[154:157], v[186:189], v[106:109]
	v_mfma_f32_16x16x32_bf16 v[94:97], v[146:149], v[194:197], v[94:97]
	v_mfma_f32_16x16x32_bf16 v[90:93], v[154:157], v[194:197], v[90:93]
	v_mfma_f32_16x16x32_bf16 v[78:81], v[146:149], v[202:205], v[78:81]
	v_mfma_f32_16x16x32_bf16 v[74:77], v[154:157], v[202:205], v[74:77]
	v_mfma_f32_16x16x32_bf16 v[126:129], v[150:153], v[182:185], v[126:129]
	v_mfma_f32_16x16x32_bf16 v[122:125], v[158:161], v[182:185], v[122:125]
	v_mfma_f32_16x16x32_bf16 v[110:113], v[150:153], v[190:193], v[110:113]
	v_mfma_f32_16x16x32_bf16 v[106:109], v[158:161], v[190:193], v[106:109]
	v_mfma_f32_16x16x32_bf16 v[94:97], v[150:153], v[198:201], v[94:97]
	v_mfma_f32_16x16x32_bf16 v[90:93], v[158:161], v[198:201], v[90:93]
	v_mfma_f32_16x16x32_bf16 v[78:81], v[150:153], v[206:209], v[78:81]
	v_mfma_f32_16x16x32_bf16 v[74:77], v[158:161], v[206:209], v[74:77]
	s_setprio 0
	s_setprio 1
	v_mfma_f32_16x16x32_bf16 v[118:121], v[162:165], v[178:181], v[118:121]
	v_mfma_f32_16x16x32_bf16 v[114:117], v[170:173], v[178:181], v[114:117]
	v_mfma_f32_16x16x32_bf16 v[102:105], v[162:165], v[186:189], v[102:105]
	v_mfma_f32_16x16x32_bf16 v[98:101], v[170:173], v[186:189], v[98:101]
	v_mfma_f32_16x16x32_bf16 v[86:89], v[162:165], v[194:197], v[86:89]
	v_mfma_f32_16x16x32_bf16 v[82:85], v[170:173], v[194:197], v[82:85]
	v_mfma_f32_16x16x32_bf16 v[70:73], v[162:165], v[202:205], v[70:73]
	v_mfma_f32_16x16x32_bf16 v[66:69], v[170:173], v[202:205], v[66:69]
	v_mfma_f32_16x16x32_bf16 v[118:121], v[166:169], v[182:185], v[118:121]
	v_mfma_f32_16x16x32_bf16 v[114:117], v[174:177], v[182:185], v[114:117]
	v_mfma_f32_16x16x32_bf16 v[102:105], v[166:169], v[190:193], v[102:105]
	v_mfma_f32_16x16x32_bf16 v[98:101], v[174:177], v[190:193], v[98:101]
	v_mfma_f32_16x16x32_bf16 v[86:89], v[166:169], v[198:201], v[86:89]
	v_mfma_f32_16x16x32_bf16 v[82:85], v[174:177], v[198:201], v[82:85]
	v_mfma_f32_16x16x32_bf16 v[70:73], v[166:169], v[206:209], v[70:73]
	v_mfma_f32_16x16x32_bf16 v[66:69], v[174:177], v[206:209], v[66:69]
	s_setprio 0
	s_barrier
	s_add_i32 s48, s49, s0
	v_lshl_add_u64 v[140:141], s[56:57], 0, v[0:1]
	s_mov_b32 m0, s48
	ds_read_b128 v[178:181], v145 offset:16384
	ds_read_b128 v[182:185], v145 offset:17408
	ds_read_b128 v[186:189], v145 offset:18432
	ds_read_b128 v[190:193], v145 offset:19456
	ds_read_b128 v[194:197], v145 offset:20480
	ds_read_b128 v[198:201], v145 offset:21504
	ds_read_b128 v[202:205], v145 offset:22528
	ds_read_b128 v[206:209], v145 offset:23552
	global_load_lds_dwordx4 v[140:141], off
	s_add_i32 m0, s48, 0x2000
	s_add_u32 s48, s56, 0x40000
	v_lshl_add_u64 v[210:211], s[56:57], 0, v[130:131]
	s_addc_u32 s49, s57, 0
	s_add_i32 s47, s47, s0
	global_load_lds_dwordx4 v[210:211], off
	v_lshl_add_u64 v[212:213], s[48:49], 0, v[0:1]
	s_mov_b32 m0, s47
	v_lshl_add_u64 v[214:215], s[58:59], 0, v[132:133]
	global_load_lds_dwordx4 v[212:213], off
	v_lshl_add_u64 v[212:213], s[48:49], 0, v[130:131]
	s_add_i32 m0, s47, 0x2000
	s_nop 0
	global_load_lds_dwordx4 v[212:213], off
	v_lshl_add_u64 v[212:213], s[58:59], 0, v[134:135]
	s_mov_b32 m0, s7
	s_nop 0
	global_load_lds_dwordx4 v[212:213], off
	s_mov_b32 m0, s8
	s_nop 0
	global_load_lds_dwordx4 v[214:215], off
	s_waitcnt vmcnt(8)
	s_waitcnt lgkmcnt(0)
	s_barrier
; #define PG8_STAGE(bufoff, gbase, voff) do { _Pragma("unroll") for (int _i = 0; _i < 2; ++_i) \
;         __builtin_amdgcn_global_load_lds((const unsigned*)((const char*)(gbase) + (voff)[_i]), (PG8_LAS unsigned*)(lds + (bufoff) + ldsw + _i * 8192), 16, 0, 0); } while (0)
; #define PG8_LDA(dst, b, h) do { _Pragma("unroll") for (int m = 0; m < 4; ++m) _Pragma("unroll") for (int k = 0; k < 2; ++k) dst[m][k] = *(const PG8_LAS bf16x8*)(lds + PG8_SA(b, h) + aoff + m * 2048 + k * 1024); } while (0)
; #define PG8_LDB(dst, b, h) do { _Pragma("unroll") for (int n = 0; n < 2; ++n) _Pragma("unroll") for (int k = 0; k < 2; ++k) dst[n][k] = *(const PG8_LAS bf16x8*)(lds + PG8_SB(b, h) + boff + n * 2048 + k * 1024); } while (0)
; #define PG8_MMA(ai, bj, At, Bt) do { __builtin_amdgcn_s_setprio(1); _Pragma("unroll") for (int m = 0; m < 4; ++m) _Pragma("unroll") for (int n = 0; n < 2; ++n) _Pragma("unroll") for (int k = 0; k < 2; ++k) \
;         acc[ai][bj][m][n] = __builtin_amdgcn_mfma_f32_16x16x32_bf16(Bt[n][k], At[m][k], acc[ai][bj][m][n], 0, 0, 0); __builtin_amdgcn_s_setprio(0); } while (0)
; #define PG8_WAIT_V(n) asm volatile("s_waitcnt vmcnt(" #n ")" ::: "memory")
; #define PG8_WAIT_L(n) asm volatile("s_waitcnt lgkmcnt(" #n ")" ::: "memory")
; #define PG8_BAR __builtin_amdgcn_s_barrier()
; #define PG8_SCHED __builtin_amdgcn_sched_barrier(0)
; template <class Epi, class Sched, bool ALIGN_EPI = false, bool SP2 = false, bool UNIFORM_NT = false>
; __device__ __forceinline__ void gemm_phase(PG8_LAS unsigned char* lds, const Gemm g, const Sched& S, const Epi& E, int tid_in) {
;     ...
;             PG8_WAIT_V(8); PG8_WAIT_L(0); PG8_BAR; PG8_MMA(1, 0, At, B0); PG8_MMA(1, 1, At, B1); PG8_BAR; PG8_SCHED;
;             PG8_LDB(B0, 1, 0); PG8_LDB(B1, 1, 1); PG8_SCHED; PG8_LDA(At, 1, 0); PG8_STAGE(PG8_SA(0, 1), a2 + hstepA, voffA);
;             PG8_WAIT_V(8); PG8_WAIT_L(0); PG8_BAR; PG8_MMA(0, 0, At, B0); PG8_MMA(0, 1, At, B1); PG8_BAR; PG8_SCHED;
	s_setprio 1
	s_waitcnt lgkmcnt(0)
	v_mfma_f32_16x16x32_bf16 v[62:65], v[146:149], v[178:181], v[62:65]
	v_mfma_f32_16x16x32_bf16 v[58:61], v[154:157], v[178:181], v[58:61]
	v_mfma_f32_16x16x32_bf16 v[46:49], v[146:149], v[186:189], v[46:49]
	v_mfma_f32_16x16x32_bf16 v[42:45], v[154:157], v[186:189], v[42:45]
	v_mfma_f32_16x16x32_bf16 v[30:33], v[146:149], v[194:197], v[30:33]
	v_mfma_f32_16x16x32_bf16 v[26:29], v[154:157], v[194:197], v[26:29]
	v_mfma_f32_16x16x32_bf16 v[14:17], v[146:149], v[202:205], v[14:17]
	v_mfma_f32_16x16x32_bf16 v[10:13], v[154:157], v[202:205], v[10:13]
	v_mfma_f32_16x16x32_bf16 v[62:65], v[150:153], v[182:185], v[62:65]
	v_mfma_f32_16x16x32_bf16 v[58:61], v[158:161], v[182:185], v[58:61]
	v_mfma_f32_16x16x32_bf16 v[46:49], v[150:153], v[190:193], v[46:49]
	v_mfma_f32_16x16x32_bf16 v[42:45], v[158:161], v[190:193], v[42:45]
	v_mfma_f32_16x16x32_bf16 v[30:33], v[150:153], v[198:201], v[30:33]
	v_mfma_f32_16x16x32_bf16 v[26:29], v[158:161], v[198:201], v[26:29]
	v_mfma_f32_16x16x32_bf16 v[14:17], v[150:153], v[206:209], v[14:17]
	v_mfma_f32_16x16x32_bf16 v[10:13], v[158:161], v[206:209], v[10:13]
	s_setprio 0
	s_setprio 1
	v_mfma_f32_16x16x32_bf16 v[54:57], v[162:165], v[178:181], v[54:57]
	v_mfma_f32_16x16x32_bf16 v[50:53], v[170:173], v[178:181], v[50:53]
	v_mfma_f32_16x16x32_bf16 v[38:41], v[162:165], v[186:189], v[38:41]
	v_mfma_f32_16x16x32_bf16 v[34:37], v[170:173], v[186:189], v[34:37]
	v_mfma_f32_16x16x32_bf16 v[22:25], v[162:165], v[194:197], v[22:25]
	v_mfma_f32_16x16x32_bf16 v[18:21], v[170:173], v[194:197], v[18:21]
	v_mfma_f32_16x16x32_bf16 v[6:9], v[162:165], v[202:205], v[6:9]
	v_mfma_f32_16x16x32_bf16 v[2:5], v[170:173], v[202:205], v[2:5]
	v_mfma_f32_16x16x32_bf16 v[54:57], v[166:169], v[182:185], v[54:57]
	v_mfma_f32_16x16x32_bf16 v[50:53], v[174:177], v[182:185], v[50:53]
	v_mfma_f32_16x16x32_bf16 v[38:41], v[166:169], v[190:193], v[38:41]
	v_mfma_f32_16x16x32_bf16 v[34:37], v[174:177], v[190:193], v[34:37]
	v_mfma_f32_16x16x32_bf16 v[22:25], v[166:169], v[198:201], v[22:25]
	v_mfma_f32_16x16x32_bf16 v[18:21], v[174:177], v[198:201], v[18:21]
	v_mfma_f32_16x16x32_bf16 v[6:9], v[166:169], v[206:209], v[6:9]
	v_mfma_f32_16x16x32_bf16 v[2:5], v[174:177], v[206:209], v[2:5]
	s_setprio 0
	s_barrier
	s_add_i32 s47, 0, 0x18000
	s_add_i32 s52, 0, 0x1c000
	v_add_u32_e32 v158, s47, v143
	v_add_u32_e32 v174, s52, v143
	ds_read_b128 v[146:149], v158
	ds_read_b128 v[150:153], v158 offset:1024
	ds_read_b128 v[154:157], v158 offset:2048
	ds_read_b128 v[158:161], v158 offset:3072
	ds_read_b128 v[162:165], v174
	ds_read_b128 v[166:169], v174 offset:1024
	ds_read_b128 v[170:173], v174 offset:2048
	ds_read_b128 v[174:177], v174 offset:3072
	s_add_u32 s48, s58, 0x40000
	s_addc_u32 s49, s59, 0
	s_mov_b32 m0, s9
	v_lshl_add_u64 v[216:217], s[48:49], 0, v[134:135]
	ds_read_b128 v[178:181], v145 offset:32768
	ds_read_b128 v[182:185], v145 offset:33792
	ds_read_b128 v[186:189], v145 offset:34816
	ds_read_b128 v[190:193], v145 offset:35840
	ds_read_b128 v[194:197], v145 offset:36864
	ds_read_b128 v[198:201], v145 offset:37888
	ds_read_b128 v[202:205], v145 offset:38912
	ds_read_b128 v[206:209], v145 offset:39936
	global_load_lds_dwordx4 v[216:217], off
	v_lshl_add_u64 v[216:217], s[48:49], 0, v[132:133]
	s_mov_b32 m0, s14
	s_nop 0
	global_load_lds_dwordx4 v[216:217], off
	s_waitcnt vmcnt(8)
	s_waitcnt lgkmcnt(0)
	s_barrier
	s_setprio 1
	s_waitcnt lgkmcnt(0)
	v_mfma_f32_16x16x32_bf16 v[126:129], v[146:149], v[178:181], v[126:129]
	v_mfma_f32_16x16x32_bf16 v[122:125], v[154:157], v[178:181], v[122:125]
	v_mfma_f32_16x16x32_bf16 v[110:113], v[146:149], v[186:189], v[110:113]
	v_mfma_f32_16x16x32_bf16 v[106:109], v[154:157], v[186:189], v[106:109]
	v_mfma_f32_16x16x32_bf16 v[94:97], v[146:149], v[194:197], v[94:97]
	v_mfma_f32_16x16x32_bf16 v[90:93], v[154:157], v[194:197], v[90:93]
	v_mfma_f32_16x16x32_bf16 v[78:81], v[146:149], v[202:205], v[78:81]
	v_mfma_f32_16x16x32_bf16 v[74:77], v[154:157], v[202:205], v[74:77]
	v_mfma_f32_16x16x32_bf16 v[126:129], v[150:153], v[182:185], v[126:129]
	v_mfma_f32_16x16x32_bf16 v[122:125], v[158:161], v[182:185], v[122:125]
	v_mfma_f32_16x16x32_bf16 v[110:113], v[150:153], v[190:193], v[110:113]
	v_mfma_f32_16x16x32_bf16 v[106:109], v[158:161], v[190:193], v[106:109]
	v_mfma_f32_16x16x32_bf16 v[94:97], v[150:153], v[198:201], v[94:97]
	v_mfma_f32_16x16x32_bf16 v[90:93], v[158:161], v[198:201], v[90:93]
	v_mfma_f32_16x16x32_bf16 v[78:81], v[150:153], v[206:209], v[78:81]
	v_mfma_f32_16x16x32_bf16 v[74:77], v[158:161], v[206:209], v[74:77]
	s_setprio 0
	s_setprio 1
	v_mfma_f32_16x16x32_bf16 v[118:121], v[162:165], v[178:181], v[118:121]
	v_mfma_f32_16x16x32_bf16 v[114:117], v[170:173], v[178:181], v[114:117]
	v_mfma_f32_16x16x32_bf16 v[102:105], v[162:165], v[186:189], v[102:105]
	v_mfma_f32_16x16x32_bf16 v[98:101], v[170:173], v[186:189], v[98:101]
	v_mfma_f32_16x16x32_bf16 v[86:89], v[162:165], v[194:197], v[86:89]
	v_mfma_f32_16x16x32_bf16 v[82:85], v[170:173], v[194:197], v[82:85]
	v_mfma_f32_16x16x32_bf16 v[70:73], v[162:165], v[202:205], v[70:73]
	v_mfma_f32_16x16x32_bf16 v[66:69], v[170:173], v[202:205], v[66:69]
	v_mfma_f32_16x16x32_bf16 v[118:121], v[166:169], v[182:185], v[118:121]
	v_mfma_f32_16x16x32_bf16 v[114:117], v[174:177], v[182:185], v[114:117]
	v_mfma_f32_16x16x32_bf16 v[102:105], v[166:169], v[190:193], v[102:105]
	v_mfma_f32_16x16x32_bf16 v[98:101], v[174:177], v[190:193], v[98:101]
	v_mfma_f32_16x16x32_bf16 v[86:89], v[166:169], v[198:201], v[86:89]
	v_mfma_f32_16x16x32_bf16 v[82:85], v[174:177], v[198:201], v[82:85]
	v_mfma_f32_16x16x32_bf16 v[70:73], v[166:169], v[206:209], v[70:73]
	v_mfma_f32_16x16x32_bf16 v[66:69], v[174:177], v[206:209], v[66:69]
	s_setprio 0
	s_barrier
; #define PG8_STAGE(bufoff, gbase, voff) do { _Pragma("unroll") for (int _i = 0; _i < 2; ++_i) \
;         __builtin_amdgcn_global_load_lds((const unsigned*)((const char*)(gbase) + (voff)[_i]), (PG8_LAS unsigned*)(lds + (bufoff) + ldsw + _i * 8192), 16, 0, 0); } while (0)
; #define PG8_LDA(dst, b, h) do { _Pragma("unroll") for (int m = 0; m < 4; ++m) _Pragma("unroll") for (int k = 0; k < 2; ++k) dst[m][k] = *(const PG8_LAS bf16x8*)(lds + PG8_SA(b, h) + aoff + m * 2048 + k * 1024); } while (0)
; #define PG8_MMA(ai, bj, At, Bt) do { __builtin_amdgcn_s_setprio(1); _Pragma("unroll") for (int m = 0; m < 4; ++m) _Pragma("unroll") for (int n = 0; n < 2; ++n) _Pragma("unroll") for (int k = 0; k < 2; ++k) \
;         acc[ai][bj][m][n] = __builtin_amdgcn_mfma_f32_16x16x32_bf16(Bt[n][k], At[m][k], acc[ai][bj][m][n], 0, 0, 0); __builtin_amdgcn_s_setprio(0); } while (0)
; #define PG8_WAIT_V(n) asm volatile("s_waitcnt vmcnt(" #n ")" ::: "memory")
; #define PG8_WAIT_L(n) asm volatile("s_waitcnt lgkmcnt(" #n ")" ::: "memory")
; #define PG8_BAR __builtin_amdgcn_s_barrier()
; #define PG8_SCHED __builtin_amdgcn_sched_barrier(0)
; template <class Epi, class Sched, bool ALIGN_EPI = false, bool SP2 = false, bool UNIFORM_NT = false>
; __device__ __forceinline__ void gemm_phase(PG8_LAS unsigned char* lds, const Gemm g, const Sched& S, const Epi& E, int tid_in) {
;     ...
;         for (int t = 0; t < nt; t += 2) {
;             const bool last = (t == nt - 2);
;             const char* a1 = cA + (size_t)(t + 1) * kstep;
;             const char* a2 = last ? nA : cA + (size_t)(t + 2) * kstep; const char* b2 = last ? nB : cB + (size_t)(t + 2) * kstep;
;     ...
;             PG8_LDA(At, 1, 1); PG8_STAGE(PG8_SB(1, 0), b3, voffB); PG8_STAGE(PG8_SB(1, 1), b3 + hstepB, voffB); PG8_STAGE(PG8_SA(1, 0), a3, voffA);
;             PG8_WAIT_V(8); PG8_WAIT_L(0); PG8_BAR; PG8_MMA(1, 0, At, B0); PG8_MMA(1, 1, At, B1); PG8_BAR; PG8_SCHED;
	s_add_i32 s47, s47, s0
	v_lshl_add_u64 v[140:141], v[140:141], 0, s[82:83]
	s_mov_b32 m0, s47
	ds_read_b128 v[178:181], v145 offset:49152
	ds_read_b128 v[182:185], v145 offset:50176
	ds_read_b128 v[186:189], v145 offset:51200
	ds_read_b128 v[190:193], v145 offset:52224
	ds_read_b128 v[194:197], v145 offset:53248
	ds_read_b128 v[198:201], v145 offset:54272
	ds_read_b128 v[202:205], v145 offset:55296
	ds_read_b128 v[206:209], v145 offset:56320
	global_load_lds_dwordx4 v[140:141], off
	s_add_i32 m0, s47, 0x2000
	s_add_u32 s48, s56, 0x40080
	v_lshl_add_u64 v[140:141], v[210:211], 0, s[82:83]
	s_addc_u32 s49, s57, 0
	s_add_i32 s47, s52, s0
	global_load_lds_dwordx4 v[140:141], off
	v_lshl_add_u64 v[140:141], s[48:49], 0, v[0:1]
	s_mov_b32 m0, s47
	s_nop 0
	global_load_lds_dwordx4 v[140:141], off
	v_lshl_add_u64 v[140:141], s[48:49], 0, v[130:131]
	s_add_i32 m0, s47, 0x2000
	s_nop 0
	global_load_lds_dwordx4 v[140:141], off
	v_lshl_add_u64 v[140:141], v[212:213], 0, s[82:83]
	s_mov_b32 m0, s15
	s_nop 0
	global_load_lds_dwordx4 v[140:141], off
	v_lshl_add_u64 v[140:141], v[214:215], 0, s[82:83]
	s_mov_b32 m0, s33
	s_nop 0
	global_load_lds_dwordx4 v[140:141], off
	s_waitcnt vmcnt(8)
	s_waitcnt lgkmcnt(0)
	s_barrier
	s_setprio 1
	s_waitcnt lgkmcnt(0)
	v_mfma_f32_16x16x32_bf16 v[62:65], v[146:149], v[178:181], v[62:65]
	v_mfma_f32_16x16x32_bf16 v[58:61], v[154:157], v[178:181], v[58:61]
	v_mfma_f32_16x16x32_bf16 v[46:49], v[146:149], v[186:189], v[46:49]
	v_mfma_f32_16x16x32_bf16 v[42:45], v[154:157], v[186:189], v[42:45]
	v_mfma_f32_16x16x32_bf16 v[30:33], v[146:149], v[194:197], v[30:33]
	v_mfma_f32_16x16x32_bf16 v[26:29], v[154:157], v[194:197], v[26:29]
	v_mfma_f32_16x16x32_bf16 v[14:17], v[146:149], v[202:205], v[14:17]
	v_mfma_f32_16x16x32_bf16 v[10:13], v[154:157], v[202:205], v[10:13]
	v_mfma_f32_16x16x32_bf16 v[62:65], v[150:153], v[182:185], v[62:65]
	v_mfma_f32_16x16x32_bf16 v[58:61], v[158:161], v[182:185], v[58:61]
	v_mfma_f32_16x16x32_bf16 v[46:49], v[150:153], v[190:193], v[46:49]
	v_mfma_f32_16x16x32_bf16 v[42:45], v[158:161], v[190:193], v[42:45]
	v_mfma_f32_16x16x32_bf16 v[30:33], v[150:153], v[198:201], v[30:33]
	v_mfma_f32_16x16x32_bf16 v[26:29], v[158:161], v[198:201], v[26:29]
	v_mfma_f32_16x16x32_bf16 v[14:17], v[150:153], v[206:209], v[14:17]
	v_mfma_f32_16x16x32_bf16 v[10:13], v[158:161], v[206:209], v[10:13]
	s_setprio 0
	s_setprio 1
	v_mfma_f32_16x16x32_bf16 v[54:57], v[162:165], v[178:181], v[54:57]
	v_mfma_f32_16x16x32_bf16 v[50:53], v[170:173], v[178:181], v[50:53]
	v_mfma_f32_16x16x32_bf16 v[38:41], v[162:165], v[186:189], v[38:41]
	v_mfma_f32_16x16x32_bf16 v[34:37], v[170:173], v[186:189], v[34:37]
	v_mfma_f32_16x16x32_bf16 v[22:25], v[162:165], v[194:197], v[22:25]
	v_mfma_f32_16x16x32_bf16 v[18:21], v[170:173], v[194:197], v[18:21]
	v_mfma_f32_16x16x32_bf16 v[6:9], v[162:165], v[202:205], v[6:9]
	v_mfma_f32_16x16x32_bf16 v[2:5], v[170:173], v[202:205], v[2:5]
	v_mfma_f32_16x16x32_bf16 v[54:57], v[166:169], v[182:185], v[54:57]
	v_mfma_f32_16x16x32_bf16 v[50:53], v[174:177], v[182:185], v[50:53]
	s_add_i32 s46, s46, 2
	v_mfma_f32_16x16x32_bf16 v[38:41], v[166:169], v[190:193], v[38:41]
	s_add_u32 s54, s54, 0x100
	v_mfma_f32_16x16x32_bf16 v[34:37], v[174:177], v[190:193], v[34:37]
	s_addc_u32 s55, s55, 0
	v_mfma_f32_16x16x32_bf16 v[22:25], v[166:169], v[198:201], v[22:25]
	s_add_u32 s43, s43, 0x100
	v_mfma_f32_16x16x32_bf16 v[18:21], v[174:177], v[198:201], v[18:21]
	s_addc_u32 s45, s45, 0
	v_mfma_f32_16x16x32_bf16 v[6:9], v[166:169], v[206:209], v[6:9]
	s_cmp_gt_u32 s46, 13
	v_mfma_f32_16x16x32_bf16 v[2:5], v[174:177], v[206:209], v[2:5]
	s_setprio 0
	s_barrier
	s_cbranch_scc0 .LBB0_54
	s_and_b64 vcc, exec, s[28:29]
	s_cbranch_vccz .LBB0_57
	s_barrier

; #define PG8_STAGE(bufoff, gbase, voff) do { _Pragma("unroll") for (int _i = 0; _i < 2; ++_i) \
;         __builtin_amdgcn_global_load_lds((const unsigned*)((const char*)(gbase) + (voff)[_i]), (PG8_LAS unsigned*)(lds + (bufoff) + ldsw + _i * 8192), 16, 0, 0); } while (0)
; #define PG8_LDA(dst, b, h) do { _Pragma("unroll") for (int m = 0; m < 4; ++m) _Pragma("unroll") for (int k = 0; k < 2; ++k) dst[m][k] = *(const PG8_LAS bf16x8*)(lds + PG8_SA(b, h) + aoff + m * 2048 + k * 1024); } while (0)
; #define PG8_LDB(dst, b, h) do { _Pragma("unroll") for (int n = 0; n < 2; ++n) _Pragma("unroll") for (int k = 0; k < 2; ++k) dst[n][k] = *(const PG8_LAS bf16x8*)(lds + PG8_SB(b, h) + boff + n * 2048 + k * 1024); } while (0)
; #define PG8_MMA(ai, bj, At, Bt) do { __builtin_amdgcn_s_setprio(1); _Pragma("unroll") for (int m = 0; m < 4; ++m) _Pragma("unroll") for (int n = 0; n < 2; ++n) _Pragma("unroll") for (int k = 0; k < 2; ++k) \
;         acc[ai][bj][m][n] = __builtin_amdgcn_mfma_f32_16x16x32_bf16(Bt[n][k], At[m][k], acc[ai][bj][m][n], 0, 0, 0); __builtin_amdgcn_s_setprio(0); } while (0)
; #define PG8_WAIT_V(n) asm volatile("s_waitcnt vmcnt(" #n ")" ::: "memory")
; template <class Epi, class Sched, bool ALIGN_EPI = false, bool SP2 = false, bool UNIFORM_NT = false>
; __device__ __forceinline__ void gemm_phase(PG8_LAS unsigned char* lds, const Gemm g, const Sched& S, const Epi& E, int tid_in) {
;     ...
;         for (int t = 0; t < nt; t += 2) {
;             const bool last = (t == nt - 2);
;             const char* a1 = cA + (size_t)(t + 1) * kstep;
;             const char* a2 = last ? nA : cA + (size_t)(t + 2) * kstep; const char* b2 = last ? nB : cB + (size_t)(t + 2) * kstep;
;             const char* a3 = a2 + kstep; const char* b3 = b2 + kstep;
;             if (last && has_next) S.a_ready(nxt);
;             if constexpr (SP2) {
;             PG8_LDB(B0, 0, 0); PG8_LDB(B1, 0, 1); PG8_SCHED; PG8_LDA(At, 0, 0); PG8_STAGE(PG8_SA(1, 1), a1 + hstepA, voffA);
;             PG8_WAIT_V(8); PG8_WAIT_L(0); PG8_BAR; PG8_MMA(0, 0, At, B0); PG8_MMA(0, 1, At, B1); PG8_BAR; PG8_SCHED;
;             PG8_LDA(At, 0, 1); PG8_STAGE(PG8_SB(0, 0), b2, voffB); PG8_STAGE(PG8_SB(0, 1), b2 + hstepB, voffB); PG8_STAGE(PG8_SA(0, 0), a2, voffA);
;             PG8_WAIT_V(8); PG8_WAIT_L(0); PG8_BAR; PG8_MMA(1, 0, At, B0); PG8_MMA(1, 1, At, B1); PG8_BAR; PG8_SCHED;
.LBB0_112:
	s_add_i32 s37, s35, 2
	s_add_u32 s40, s10, 0x80
	s_addc_u32 s41, s11, 0
	s_add_i32 s43, 0, 0x10000
	s_cmp_eq_u32 s12, s35
	s_cselect_b32 s41, s85, s41
	s_cselect_b32 s40, s84, s40
	s_cselect_b32 s45, s69, s31
	s_cselect_b32 s44, s68, s13
	s_add_i32 s35, 0, 0x14000
	v_add_u32_e32 v142, s43, v243
	v_add_u32_e32 v158, s35, v243
	ds_read_b128 v[130:133], v142
	ds_read_b128 v[134:137], v142 offset:1024
	ds_read_b128 v[138:141], v142 offset:2048
	ds_read_b128 v[142:145], v142 offset:3072
	ds_read_b128 v[146:149], v158
	ds_read_b128 v[150:153], v158 offset:1024
	ds_read_b128 v[154:157], v158 offset:2048
	ds_read_b128 v[158:161], v158 offset:3072
	v_lshl_add_u64 v[204:205], s[10:11], 0, v[184:185]
	s_add_i32 m0, s64, 0xc000
	ds_read_b128 v[162:165], v244
	ds_read_b128 v[166:169], v244 offset:1024
	ds_read_b128 v[170:173], v244 offset:2048
	ds_read_b128 v[174:177], v244 offset:3072
	ds_read_b128 v[188:191], v244 offset:4096
	ds_read_b128 v[192:195], v244 offset:5120
	ds_read_b128 v[196:199], v244 offset:6144
	ds_read_b128 v[200:203], v244 offset:7168
	global_load_lds_dwordx4 v[204:205], off
	v_lshl_add_u64 v[204:205], s[10:11], 0, v[186:187]
	s_add_i32 m0, s64, 0xe000
	s_nop 0
	global_load_lds_dwordx4 v[204:205], off
	s_waitcnt vmcnt(8)
	s_waitcnt lgkmcnt(0)
	s_barrier
	s_setprio 1
	s_waitcnt lgkmcnt(0)
	v_mfma_f32_16x16x32_bf16 v[126:129], v[130:133], v[162:165], v[126:129]
	v_mfma_f32_16x16x32_bf16 v[122:125], v[138:141], v[162:165], v[122:125]
	v_mfma_f32_16x16x32_bf16 v[118:121], v[130:133], v[170:173], v[118:121]
	v_mfma_f32_16x16x32_bf16 v[114:117], v[138:141], v[170:173], v[114:117]
	v_mfma_f32_16x16x32_bf16 v[110:113], v[130:133], v[188:191], v[110:113]
	v_mfma_f32_16x16x32_bf16 v[106:109], v[138:141], v[188:191], v[106:109]
	v_mfma_f32_16x16x32_bf16 v[102:105], v[130:133], v[196:199], v[102:105]
	v_mfma_f32_16x16x32_bf16 v[98:101], v[138:141], v[196:199], v[98:101]
	v_mfma_f32_16x16x32_bf16 v[126:129], v[134:137], v[166:169], v[126:129]
	v_mfma_f32_16x16x32_bf16 v[122:125], v[142:145], v[166:169], v[122:125]
	v_mfma_f32_16x16x32_bf16 v[118:121], v[134:137], v[174:177], v[118:121]
	v_mfma_f32_16x16x32_bf16 v[114:117], v[142:145], v[174:177], v[114:117]
	v_mfma_f32_16x16x32_bf16 v[110:113], v[134:137], v[192:195], v[110:113]
	v_mfma_f32_16x16x32_bf16 v[106:109], v[142:145], v[192:195], v[106:109]
	v_mfma_f32_16x16x32_bf16 v[102:105], v[134:137], v[200:203], v[102:105]
	v_mfma_f32_16x16x32_bf16 v[98:101], v[142:145], v[200:203], v[98:101]
	s_setprio 0
	s_setprio 1
	v_mfma_f32_16x16x32_bf16 v[62:65], v[146:149], v[162:165], v[62:65]
	v_mfma_f32_16x16x32_bf16 v[58:61], v[154:157], v[162:165], v[58:61]
	v_mfma_f32_16x16x32_bf16 v[54:57], v[146:149], v[170:173], v[54:57]
	v_mfma_f32_16x16x32_bf16 v[50:53], v[154:157], v[170:173], v[50:53]
	v_mfma_f32_16x16x32_bf16 v[46:49], v[146:149], v[188:191], v[46:49]
	v_mfma_f32_16x16x32_bf16 v[42:45], v[154:157], v[188:191], v[42:45]
	v_mfma_f32_16x16x32_bf16 v[38:41], v[146:149], v[196:199], v[38:41]
	v_mfma_f32_16x16x32_bf16 v[34:37], v[154:157], v[196:199], v[34:37]
	v_mfma_f32_16x16x32_bf16 v[62:65], v[150:153], v[166:169], v[62:65]
	v_mfma_f32_16x16x32_bf16 v[58:61], v[158:161], v[166:169], v[58:61]
	v_mfma_f32_16x16x32_bf16 v[54:57], v[150:153], v[174:177], v[54:57]
	v_mfma_f32_16x16x32_bf16 v[50:53], v[158:161], v[174:177], v[50:53]
	v_mfma_f32_16x16x32_bf16 v[46:49], v[150:153], v[192:195], v[46:49]
	v_mfma_f32_16x16x32_bf16 v[42:45], v[158:161], v[192:195], v[42:45]
	v_mfma_f32_16x16x32_bf16 v[38:41], v[150:153], v[200:203], v[38:41]
	v_mfma_f32_16x16x32_bf16 v[34:37], v[158:161], v[200:203], v[34:37]
	s_setprio 0
	s_barrier
	s_add_i32 s43, s43, s49
	v_lshl_add_u64 v[204:205], s[44:45], 0, v[0:1]
	s_mov_b32 m0, s43
	ds_read_b128 v[162:165], v244 offset:16384
	ds_read_b128 v[166:169], v244 offset:17408
	ds_read_b128 v[170:173], v244 offset:18432
	ds_read_b128 v[174:177], v244 offset:19456
	ds_read_b128 v[188:191], v244 offset:20480
	ds_read_b128 v[192:195], v244 offset:21504
	ds_read_b128 v[196:199], v244 offset:22528
	ds_read_b128 v[200:203], v244 offset:23552
	global_load_lds_dwordx4 v[204:205], off
	s_add_i32 m0, s43, 0x2000
	v_lshl_add_u64 v[206:207], s[44:45], 0, v[182:183]
	s_add_u32 s44, s44, s26
	s_addc_u32 s45, s45, 0
	s_add_i32 s35, s35, s49
	global_load_lds_dwordx4 v[206:207], off
	v_lshl_add_u64 v[208:209], s[44:45], 0, v[0:1]
	s_mov_b32 m0, s35
	v_lshl_add_u64 v[210:211], s[44:45], 0, v[182:183]
	global_load_lds_dwordx4 v[208:209], off
	s_add_i32 m0, s35, 0x2000
	v_lshl_add_u64 v[212:213], s[40:41], 0, v[178:179]
	global_load_lds_dwordx4 v[210:211], off
	s_mov_b32 m0, s64
	v_lshl_add_u64 v[214:215], s[40:41], 0, v[180:181]
	global_load_lds_dwordx4 v[212:213], off
	s_mov_b32 m0, s78
	s_nop 0
	global_load_lds_dwordx4 v[214:215], off
	s_waitcnt vmcnt(8)
	s_waitcnt lgkmcnt(0)
	s_barrier
; #define PG8_STAGE(bufoff, gbase, voff) do { _Pragma("unroll") for (int _i = 0; _i < 2; ++_i) \
;         __builtin_amdgcn_global_load_lds((const unsigned*)((const char*)(gbase) + (voff)[_i]), (PG8_LAS unsigned*)(lds + (bufoff) + ldsw + _i * 8192), 16, 0, 0); } while (0)
; #define PG8_LDA(dst, b, h) do { _Pragma("unroll") for (int m = 0; m < 4; ++m) _Pragma("unroll") for (int k = 0; k < 2; ++k) dst[m][k] = *(const PG8_LAS bf16x8*)(lds + PG8_SA(b, h) + aoff + m * 2048 + k * 1024); } while (0)
; #define PG8_LDB(dst, b, h) do { _Pragma("unroll") for (int n = 0; n < 2; ++n) _Pragma("unroll") for (int k = 0; k < 2; ++k) dst[n][k] = *(const PG8_LAS bf16x8*)(lds + PG8_SB(b, h) + boff + n * 2048 + k * 1024); } while (0)
; #define PG8_MMA(ai, bj, At, Bt) do { __builtin_amdgcn_s_setprio(1); _Pragma("unroll") for (int m = 0; m < 4; ++m) _Pragma("unroll") for (int n = 0; n < 2; ++n) _Pragma("unroll") for (int k = 0; k < 2; ++k) \
;         acc[ai][bj][m][n] = __builtin_amdgcn_mfma_f32_16x16x32_bf16(Bt[n][k], At[m][k], acc[ai][bj][m][n], 0, 0, 0); __builtin_amdgcn_s_setprio(0); } while (0)
; #define PG8_WAIT_V(n) asm volatile("s_waitcnt vmcnt(" #n ")" ::: "memory")
; #define PG8_WAIT_L(n) asm volatile("s_waitcnt lgkmcnt(" #n ")" ::: "memory")
; #define PG8_BAR __builtin_amdgcn_s_barrier()
; #define PG8_SCHED __builtin_amdgcn_sched_barrier(0)
; template <class Epi, class Sched, bool ALIGN_EPI = false, bool SP2 = false, bool UNIFORM_NT = false>
; __device__ __forceinline__ void gemm_phase(PG8_LAS unsigned char* lds, const Gemm g, const Sched& S, const Epi& E, int tid_in) {
;     ...
;             PG8_WAIT_V(8); PG8_WAIT_L(0); PG8_BAR; PG8_MMA(1, 0, At, B0); PG8_MMA(1, 1, At, B1); PG8_BAR; PG8_SCHED;
;             PG8_LDB(B0, 1, 0); PG8_LDB(B1, 1, 1); PG8_SCHED; PG8_LDA(At, 1, 0); PG8_STAGE(PG8_SA(0, 1), a2 + hstepA, voffA);
;             PG8_WAIT_V(8); PG8_WAIT_L(0); PG8_BAR; PG8_MMA(0, 0, At, B0); PG8_MMA(0, 1, At, B1); PG8_BAR; PG8_SCHED;
	s_setprio 1
	s_waitcnt lgkmcnt(0)
	v_mfma_f32_16x16x32_bf16 v[94:97], v[130:133], v[162:165], v[94:97]
	v_mfma_f32_16x16x32_bf16 v[90:93], v[138:141], v[162:165], v[90:93]
	v_mfma_f32_16x16x32_bf16 v[86:89], v[130:133], v[170:173], v[86:89]
	v_mfma_f32_16x16x32_bf16 v[82:85], v[138:141], v[170:173], v[82:85]
	v_mfma_f32_16x16x32_bf16 v[78:81], v[130:133], v[188:191], v[78:81]
	v_mfma_f32_16x16x32_bf16 v[74:77], v[138:141], v[188:191], v[74:77]
	v_mfma_f32_16x16x32_bf16 v[70:73], v[130:133], v[196:199], v[70:73]
	v_mfma_f32_16x16x32_bf16 v[66:69], v[138:141], v[196:199], v[66:69]
	v_mfma_f32_16x16x32_bf16 v[94:97], v[134:137], v[166:169], v[94:97]
	v_mfma_f32_16x16x32_bf16 v[90:93], v[142:145], v[166:169], v[90:93]
	v_mfma_f32_16x16x32_bf16 v[86:89], v[134:137], v[174:177], v[86:89]
	v_mfma_f32_16x16x32_bf16 v[82:85], v[142:145], v[174:177], v[82:85]
	v_mfma_f32_16x16x32_bf16 v[78:81], v[134:137], v[192:195], v[78:81]
	v_mfma_f32_16x16x32_bf16 v[74:77], v[142:145], v[192:195], v[74:77]
	v_mfma_f32_16x16x32_bf16 v[70:73], v[134:137], v[200:203], v[70:73]
	v_mfma_f32_16x16x32_bf16 v[66:69], v[142:145], v[200:203], v[66:69]
	s_setprio 0
	s_setprio 1
	v_mfma_f32_16x16x32_bf16 v[30:33], v[146:149], v[162:165], v[30:33]
	v_mfma_f32_16x16x32_bf16 v[26:29], v[154:157], v[162:165], v[26:29]
	v_mfma_f32_16x16x32_bf16 v[22:25], v[146:149], v[170:173], v[22:25]
	v_mfma_f32_16x16x32_bf16 v[18:21], v[154:157], v[170:173], v[18:21]
	v_mfma_f32_16x16x32_bf16 v[14:17], v[146:149], v[188:191], v[14:17]
	v_mfma_f32_16x16x32_bf16 v[10:13], v[154:157], v[188:191], v[10:13]
	v_mfma_f32_16x16x32_bf16 v[6:9], v[146:149], v[196:199], v[6:9]
	v_mfma_f32_16x16x32_bf16 v[2:5], v[154:157], v[196:199], v[2:5]
	v_mfma_f32_16x16x32_bf16 v[30:33], v[150:153], v[166:169], v[30:33]
	v_mfma_f32_16x16x32_bf16 v[26:29], v[158:161], v[166:169], v[26:29]
	v_mfma_f32_16x16x32_bf16 v[22:25], v[150:153], v[174:177], v[22:25]
	v_mfma_f32_16x16x32_bf16 v[18:21], v[158:161], v[174:177], v[18:21]
	v_mfma_f32_16x16x32_bf16 v[14:17], v[150:153], v[192:195], v[14:17]
	v_mfma_f32_16x16x32_bf16 v[10:13], v[158:161], v[192:195], v[10:13]
	v_mfma_f32_16x16x32_bf16 v[6:9], v[150:153], v[200:203], v[6:9]
	v_mfma_f32_16x16x32_bf16 v[2:5], v[158:161], v[200:203], v[2:5]
	s_setprio 0
	s_barrier
	s_add_i32 s35, 0, 0x18000
	s_add_i32 s43, 0, 0x1c000
	v_add_u32_e32 v142, s35, v243
	v_add_u32_e32 v158, s43, v243
	ds_read_b128 v[130:133], v142
	ds_read_b128 v[134:137], v142 offset:1024
	ds_read_b128 v[138:141], v142 offset:2048
	ds_read_b128 v[142:145], v142 offset:3072
	ds_read_b128 v[146:149], v158
	ds_read_b128 v[150:153], v158 offset:1024
	ds_read_b128 v[154:157], v158 offset:2048
	ds_read_b128 v[158:161], v158 offset:3072
	s_add_u32 s40, s40, s26
	s_addc_u32 s41, s41, 0
	s_mov_b32 m0, s79
	v_lshl_add_u64 v[216:217], s[40:41], 0, v[178:179]
	ds_read_b128 v[162:165], v244 offset:32768
	ds_read_b128 v[166:169], v244 offset:33792
	ds_read_b128 v[170:173], v244 offset:34816
	ds_read_b128 v[174:177], v244 offset:35840
	ds_read_b128 v[188:191], v244 offset:36864
	ds_read_b128 v[192:195], v244 offset:37888
	ds_read_b128 v[196:199], v244 offset:38912
	ds_read_b128 v[200:203], v244 offset:39936
	global_load_lds_dwordx4 v[216:217], off
	v_lshl_add_u64 v[216:217], s[40:41], 0, v[180:181]
	s_mov_b32 m0, s88
	s_nop 0
	global_load_lds_dwordx4 v[216:217], off
	s_waitcnt vmcnt(8)
	s_waitcnt lgkmcnt(0)
	s_barrier
	s_setprio 1
	s_waitcnt lgkmcnt(0)
	v_mfma_f32_16x16x32_bf16 v[126:129], v[130:133], v[162:165], v[126:129]
	v_mfma_f32_16x16x32_bf16 v[122:125], v[138:141], v[162:165], v[122:125]
	v_mfma_f32_16x16x32_bf16 v[118:121], v[130:133], v[170:173], v[118:121]
	v_mfma_f32_16x16x32_bf16 v[114:117], v[138:141], v[170:173], v[114:117]
	v_mfma_f32_16x16x32_bf16 v[110:113], v[130:133], v[188:191], v[110:113]
	v_mfma_f32_16x16x32_bf16 v[106:109], v[138:141], v[188:191], v[106:109]
	v_mfma_f32_16x16x32_bf16 v[102:105], v[130:133], v[196:199], v[102:105]
	v_mfma_f32_16x16x32_bf16 v[98:101], v[138:141], v[196:199], v[98:101]
	v_mfma_f32_16x16x32_bf16 v[126:129], v[134:137], v[166:169], v[126:129]
	v_mfma_f32_16x16x32_bf16 v[122:125], v[142:145], v[166:169], v[122:125]
	v_mfma_f32_16x16x32_bf16 v[118:121], v[134:137], v[174:177], v[118:121]
	v_mfma_f32_16x16x32_bf16 v[114:117], v[142:145], v[174:177], v[114:117]
	v_mfma_f32_16x16x32_bf16 v[110:113], v[134:137], v[192:195], v[110:113]
	v_mfma_f32_16x16x32_bf16 v[106:109], v[142:145], v[192:195], v[106:109]
	v_mfma_f32_16x16x32_bf16 v[102:105], v[134:137], v[200:203], v[102:105]
	v_mfma_f32_16x16x32_bf16 v[98:101], v[142:145], v[200:203], v[98:101]
	s_setprio 0
	s_setprio 1
	v_mfma_f32_16x16x32_bf16 v[62:65], v[146:149], v[162:165], v[62:65]
	v_mfma_f32_16x16x32_bf16 v[58:61], v[154:157], v[162:165], v[58:61]
	v_mfma_f32_16x16x32_bf16 v[54:57], v[146:149], v[170:173], v[54:57]
	v_mfma_f32_16x16x32_bf16 v[50:53], v[154:157], v[170:173], v[50:53]
	v_mfma_f32_16x16x32_bf16 v[46:49], v[146:149], v[188:191], v[46:49]
	v_mfma_f32_16x16x32_bf16 v[42:45], v[154:157], v[188:191], v[42:45]
	v_mfma_f32_16x16x32_bf16 v[38:41], v[146:149], v[196:199], v[38:41]
	v_mfma_f32_16x16x32_bf16 v[34:37], v[154:157], v[196:199], v[34:37]
	v_mfma_f32_16x16x32_bf16 v[62:65], v[150:153], v[166:169], v[62:65]
	v_mfma_f32_16x16x32_bf16 v[58:61], v[158:161], v[166:169], v[58:61]
	v_mfma_f32_16x16x32_bf16 v[54:57], v[150:153], v[174:177], v[54:57]
	v_mfma_f32_16x16x32_bf16 v[50:53], v[158:161], v[174:177], v[50:53]
	v_mfma_f32_16x16x32_bf16 v[46:49], v[150:153], v[192:195], v[46:49]
	v_mfma_f32_16x16x32_bf16 v[42:45], v[158:161], v[192:195], v[42:45]
	v_mfma_f32_16x16x32_bf16 v[38:41], v[150:153], v[200:203], v[38:41]
	v_mfma_f32_16x16x32_bf16 v[34:37], v[158:161], v[200:203], v[34:37]
	s_setprio 0
	s_barrier
; #define PG8_STAGE(bufoff, gbase, voff) do { _Pragma("unroll") for (int _i = 0; _i < 2; ++_i) \
;         __builtin_amdgcn_global_load_lds((const unsigned*)((const char*)(gbase) + (voff)[_i]), (PG8_LAS unsigned*)(lds + (bufoff) + ldsw + _i * 8192), 16, 0, 0); } while (0)
; #define PG8_LDA(dst, b, h) do { _Pragma("unroll") for (int m = 0; m < 4; ++m) _Pragma("unroll") for (int k = 0; k < 2; ++k) dst[m][k] = *(const PG8_LAS bf16x8*)(lds + PG8_SA(b, h) + aoff + m * 2048 + k * 1024); } while (0)
; #define PG8_MMA(ai, bj, At, Bt) do { __builtin_amdgcn_s_setprio(1); _Pragma("unroll") for (int m = 0; m < 4; ++m) _Pragma("unroll") for (int n = 0; n < 2; ++n) _Pragma("unroll") for (int k = 0; k < 2; ++k) \
;         acc[ai][bj][m][n] = __builtin_amdgcn_mfma_f32_16x16x32_bf16(Bt[n][k], At[m][k], acc[ai][bj][m][n], 0, 0, 0); __builtin_amdgcn_s_setprio(0); } while (0)
; #define PG8_WAIT_V(n) asm volatile("s_waitcnt vmcnt(" #n ")" ::: "memory")
; #define PG8_WAIT_L(n) asm volatile("s_waitcnt lgkmcnt(" #n ")" ::: "memory")
; #define PG8_BAR __builtin_amdgcn_s_barrier()
; #define PG8_SCHED __builtin_amdgcn_sched_barrier(0)
; template <class Epi, class Sched, bool ALIGN_EPI = false, bool SP2 = false, bool UNIFORM_NT = false>
; __device__ __forceinline__ void gemm_phase(PG8_LAS unsigned char* lds, const Gemm g, const Sched& S, const Epi& E, int tid_in) {
;     ...
;         for (int t = 0; t < nt; t += 2) {
;             const bool last = (t == nt - 2);
;             const char* a1 = cA + (size_t)(t + 1) * kstep;
;             const char* a2 = last ? nA : cA + (size_t)(t + 2) * kstep; const char* b2 = last ? nB : cB + (size_t)(t + 2) * kstep;
;     ...
;             PG8_LDA(At, 1, 1); PG8_STAGE(PG8_SB(1, 0), b3, voffB); PG8_STAGE(PG8_SB(1, 1), b3 + hstepB, voffB); PG8_STAGE(PG8_SA(1, 0), a3, voffA);
;             PG8_WAIT_V(8); PG8_WAIT_L(0); PG8_BAR; PG8_MMA(1, 0, At, B0); PG8_MMA(1, 1, At, B1); PG8_BAR; PG8_SCHED;
	s_add_i32 s35, s35, s49
	v_lshl_add_u64 v[204:205], v[204:205], 0, s[82:83]
	s_mov_b32 m0, s35
	ds_read_b128 v[162:165], v244 offset:49152
	ds_read_b128 v[166:169], v244 offset:50176
	ds_read_b128 v[170:173], v244 offset:51200
	ds_read_b128 v[174:177], v244 offset:52224
	ds_read_b128 v[188:191], v244 offset:53248
	ds_read_b128 v[192:195], v244 offset:54272
	ds_read_b128 v[196:199], v244 offset:55296
	ds_read_b128 v[200:203], v244 offset:56320
	global_load_lds_dwordx4 v[204:205], off
	v_lshl_add_u64 v[204:205], v[206:207], 0, s[82:83]
	s_add_i32 m0, s35, 0x2000
	s_add_i32 s35, s43, s49
	global_load_lds_dwordx4 v[204:205], off
	v_lshl_add_u64 v[204:205], v[208:209], 0, s[82:83]
	s_mov_b32 m0, s35
	s_nop 0
	global_load_lds_dwordx4 v[204:205], off
	v_lshl_add_u64 v[204:205], v[210:211], 0, s[82:83]
	s_add_i32 m0, s35, 0x2000
	s_nop 0
	global_load_lds_dwordx4 v[204:205], off
	v_lshl_add_u64 v[204:205], v[212:213], 0, s[82:83]
	s_mov_b32 m0, s94
	s_nop 0
	global_load_lds_dwordx4 v[204:205], off
	v_lshl_add_u64 v[204:205], v[214:215], 0, s[82:83]
	s_mov_b32 m0, s89
	s_nop 0
	global_load_lds_dwordx4 v[204:205], off
	s_waitcnt vmcnt(8)
	s_waitcnt lgkmcnt(0)
	s_barrier
	s_setprio 1
	s_waitcnt lgkmcnt(0)
	v_mfma_f32_16x16x32_bf16 v[94:97], v[130:133], v[162:165], v[94:97]
	v_mfma_f32_16x16x32_bf16 v[90:93], v[138:141], v[162:165], v[90:93]
	v_mfma_f32_16x16x32_bf16 v[86:89], v[130:133], v[170:173], v[86:89]
	v_mfma_f32_16x16x32_bf16 v[82:85], v[138:141], v[170:173], v[82:85]
	v_mfma_f32_16x16x32_bf16 v[78:81], v[130:133], v[188:191], v[78:81]
	v_mfma_f32_16x16x32_bf16 v[74:77], v[138:141], v[188:191], v[74:77]
	v_mfma_f32_16x16x32_bf16 v[70:73], v[130:133], v[196:199], v[70:73]
	v_mfma_f32_16x16x32_bf16 v[66:69], v[138:141], v[196:199], v[66:69]
	v_mfma_f32_16x16x32_bf16 v[94:97], v[134:137], v[166:169], v[94:97]
	v_mfma_f32_16x16x32_bf16 v[90:93], v[142:145], v[166:169], v[90:93]
	v_mfma_f32_16x16x32_bf16 v[86:89], v[134:137], v[174:177], v[86:89]
	v_mfma_f32_16x16x32_bf16 v[82:85], v[142:145], v[174:177], v[82:85]
	v_mfma_f32_16x16x32_bf16 v[78:81], v[134:137], v[192:195], v[78:81]
	v_mfma_f32_16x16x32_bf16 v[74:77], v[142:145], v[192:195], v[74:77]
	v_mfma_f32_16x16x32_bf16 v[70:73], v[134:137], v[200:203], v[70:73]
	v_mfma_f32_16x16x32_bf16 v[66:69], v[142:145], v[200:203], v[66:69]
	s_setprio 0
	s_setprio 1
	v_mfma_f32_16x16x32_bf16 v[30:33], v[146:149], v[162:165], v[30:33]
	v_mfma_f32_16x16x32_bf16 v[26:29], v[154:157], v[162:165], v[26:29]
	v_mfma_f32_16x16x32_bf16 v[22:25], v[146:149], v[170:173], v[22:25]
	v_mfma_f32_16x16x32_bf16 v[18:21], v[154:157], v[170:173], v[18:21]
	v_mfma_f32_16x16x32_bf16 v[14:17], v[146:149], v[188:191], v[14:17]
	v_mfma_f32_16x16x32_bf16 v[10:13], v[154:157], v[188:191], v[10:13]
	v_mfma_f32_16x16x32_bf16 v[6:9], v[146:149], v[196:199], v[6:9]
	v_mfma_f32_16x16x32_bf16 v[2:5], v[154:157], v[196:199], v[2:5]
	v_mfma_f32_16x16x32_bf16 v[30:33], v[150:153], v[166:169], v[30:33]
	v_mfma_f32_16x16x32_bf16 v[26:29], v[158:161], v[166:169], v[26:29]
	s_add_u32 s10, s10, 0x100
	v_mfma_f32_16x16x32_bf16 v[22:25], v[150:153], v[174:177], v[22:25]
	s_addc_u32 s11, s11, 0
	v_mfma_f32_16x16x32_bf16 v[18:21], v[158:161], v[174:177], v[18:21]
	s_add_u32 s13, s13, 0x100
	v_mfma_f32_16x16x32_bf16 v[14:17], v[150:153], v[192:195], v[14:17]
	s_addc_u32 s31, s31, 0
	v_mfma_f32_16x16x32_bf16 v[10:13], v[158:161], v[192:195], v[10:13]
	s_cmp_ge_i32 s37, s15
	v_mfma_f32_16x16x32_bf16 v[6:9], v[150:153], v[200:203], v[6:9]
	s_mov_b32 s35, s37
	v_mfma_f32_16x16x32_bf16 v[2:5], v[158:161], v[200:203], v[2:5]
	s_setprio 0
	s_barrier
	s_cbranch_scc0 .LBB0_112
	s_and_b64 vcc, exec, s[62:63]
	s_cbranch_vccz .LBB0_115
	s_barrier

; #define PG8_STAGE(bufoff, gbase, voff) do { _Pragma("unroll") for (int _i = 0; _i < 2; ++_i) \
;         __builtin_amdgcn_global_load_lds((const unsigned*)((const char*)(gbase) + (voff)[_i]), (PG8_LAS unsigned*)(lds + (bufoff) + ldsw + _i * 8192), 16, 0, 0); } while (0)
; #define PG8_LDA(dst, b, h) do { _Pragma("unroll") for (int m = 0; m < 4; ++m) _Pragma("unroll") for (int k = 0; k < 2; ++k) dst[m][k] = *(const PG8_LAS bf16x8*)(lds + PG8_SA(b, h) + aoff + m * 2048 + k * 1024); } while (0)
; #define PG8_LDB(dst, b, h) do { _Pragma("unroll") for (int n = 0; n < 2; ++n) _Pragma("unroll") for (int k = 0; k < 2; ++k) dst[n][k] = *(const PG8_LAS bf16x8*)(lds + PG8_SB(b, h) + boff + n * 2048 + k * 1024); } while (0)
; #define PG8_MMA(ai, bj, At, Bt) do { __builtin_amdgcn_s_setprio(1); _Pragma("unroll") for (int m = 0; m < 4; ++m) _Pragma("unroll") for (int n = 0; n < 2; ++n) _Pragma("unroll") for (int k = 0; k < 2; ++k) \
;         acc[ai][bj][m][n] = __builtin_amdgcn_mfma_f32_16x16x32_bf16(Bt[n][k], At[m][k], acc[ai][bj][m][n], 0, 0, 0); __builtin_amdgcn_s_setprio(0); } while (0)
; #define PG8_WAIT_V(n) asm volatile("s_waitcnt vmcnt(" #n ")" ::: "memory")
; template <class Epi, class Sched, bool ALIGN_EPI = false, bool SP2 = false, bool UNIFORM_NT = false>
; __device__ __forceinline__ void gemm_phase(PG8_LAS unsigned char* lds, const Gemm g, const Sched& S, const Epi& E, int tid_in) {
;     ...
;         for (int t = 0; t < nt; t += 2) {
;             const bool last = (t == nt - 2);
;             const char* a1 = cA + (size_t)(t + 1) * kstep;
;             const char* a2 = last ? nA : cA + (size_t)(t + 2) * kstep; const char* b2 = last ? nB : cB + (size_t)(t + 2) * kstep;
;             const char* a3 = a2 + kstep; const char* b3 = b2 + kstep;
;             if (last && has_next) S.a_ready(nxt);
;             if constexpr (SP2) {
;             PG8_LDB(B0, 0, 0); PG8_LDB(B1, 0, 1); PG8_SCHED; PG8_LDA(At, 0, 0); PG8_STAGE(PG8_SA(1, 1), a1 + hstepA, voffA);
;             PG8_WAIT_V(8); PG8_WAIT_L(0); PG8_BAR; PG8_MMA(0, 0, At, B0); PG8_MMA(0, 1, At, B1); PG8_BAR; PG8_SCHED;
;             PG8_LDA(At, 0, 1); PG8_STAGE(PG8_SB(0, 0), b2, voffB); PG8_STAGE(PG8_SB(0, 1), b2 + hstepB, voffB); PG8_STAGE(PG8_SA(0, 0), a2, voffA);
;             PG8_WAIT_V(8); PG8_WAIT_L(0); PG8_BAR; PG8_MMA(1, 0, At, B0); PG8_MMA(1, 1, At, B1); PG8_BAR; PG8_SCHED;
.LBB0_833:
	s_add_u32 s26, s24, 0xfffc0080
	s_addc_u32 s27, s25, -1
	s_add_i32 s40, 0, 0x10000
	s_cmp_eq_u32 s37, 12
	s_cselect_b32 s29, s11, s27
	s_cselect_b32 s28, s12, s26
	s_cselect_b32 s27, s13, s36
	s_cselect_b32 s26, s19, s35
	s_add_i32 s42, 0, 0x14000
	v_add_u32_e32 v156, s40, v145
	v_add_u32_e32 v164, s42, v145
	ds_read_b128 v[140:143], v156
	ds_read_b128 v[148:151], v156 offset:1024
	ds_read_b128 v[152:155], v156 offset:2048
	ds_read_b128 v[156:159], v156 offset:3072
	ds_read_b128 v[160:163], v164
	ds_read_b128 v[178:181], v164 offset:1024
	ds_read_b128 v[182:185], v164 offset:2048
	ds_read_b128 v[186:189], v164 offset:3072
	v_lshl_add_u64 v[164:165], s[24:25], 0, v[136:137]
	s_add_i32 m0, s8, 0xc000
	ds_read_b128 v[190:193], v147
	ds_read_b128 v[194:197], v147 offset:1024
	ds_read_b128 v[198:201], v147 offset:2048
	ds_read_b128 v[202:205], v147 offset:3072
	ds_read_b128 v[206:209], v147 offset:4096
	ds_read_b128 v[210:213], v147 offset:5120
	ds_read_b128 v[214:217], v147 offset:6144
	ds_read_b128 v[218:221], v147 offset:7168
	global_load_lds_dwordx4 v[164:165], off
	v_lshl_add_u64 v[164:165], s[24:25], 0, v[138:139]
	s_add_i32 m0, s8, 0xe000
	s_nop 0
	global_load_lds_dwordx4 v[164:165], off
	s_waitcnt vmcnt(8)
	s_waitcnt lgkmcnt(0)
	s_barrier
	s_setprio 1
	s_waitcnt lgkmcnt(0)
	v_mfma_f32_16x16x32_bf16 v[126:129], v[140:143], v[190:193], v[126:129]
	v_mfma_f32_16x16x32_bf16 v[122:125], v[152:155], v[190:193], v[122:125]
	v_mfma_f32_16x16x32_bf16 v[118:121], v[140:143], v[198:201], v[118:121]
	v_mfma_f32_16x16x32_bf16 v[110:113], v[152:155], v[198:201], v[110:113]
	v_mfma_f32_16x16x32_bf16 v[102:105], v[140:143], v[206:209], v[102:105]
	v_mfma_f32_16x16x32_bf16 v[94:97], v[152:155], v[206:209], v[94:97]
	v_mfma_f32_16x16x32_bf16 v[86:89], v[140:143], v[214:217], v[86:89]
	v_mfma_f32_16x16x32_bf16 v[78:81], v[152:155], v[214:217], v[78:81]
	v_mfma_f32_16x16x32_bf16 v[126:129], v[148:151], v[194:197], v[126:129]
	v_mfma_f32_16x16x32_bf16 v[122:125], v[156:159], v[194:197], v[122:125]
	v_mfma_f32_16x16x32_bf16 v[118:121], v[148:151], v[202:205], v[118:121]
	v_mfma_f32_16x16x32_bf16 v[110:113], v[156:159], v[202:205], v[110:113]
	v_mfma_f32_16x16x32_bf16 v[102:105], v[148:151], v[210:213], v[102:105]
	v_mfma_f32_16x16x32_bf16 v[94:97], v[156:159], v[210:213], v[94:97]
	v_mfma_f32_16x16x32_bf16 v[86:89], v[148:151], v[218:221], v[86:89]
	v_mfma_f32_16x16x32_bf16 v[78:81], v[156:159], v[218:221], v[78:81]
	s_setprio 0
	s_setprio 1
	v_mfma_f32_16x16x32_bf16 v[114:117], v[160:163], v[190:193], v[114:117]
	v_mfma_f32_16x16x32_bf16 v[106:109], v[182:185], v[190:193], v[106:109]
	v_mfma_f32_16x16x32_bf16 v[98:101], v[160:163], v[198:201], v[98:101]
	v_mfma_f32_16x16x32_bf16 v[90:93], v[182:185], v[198:201], v[90:93]
	v_mfma_f32_16x16x32_bf16 v[82:85], v[160:163], v[206:209], v[82:85]
	v_mfma_f32_16x16x32_bf16 v[74:77], v[182:185], v[206:209], v[74:77]
	v_mfma_f32_16x16x32_bf16 v[70:73], v[160:163], v[214:217], v[70:73]
	v_mfma_f32_16x16x32_bf16 v[66:69], v[182:185], v[214:217], v[66:69]
	v_mfma_f32_16x16x32_bf16 v[114:117], v[178:181], v[194:197], v[114:117]
	v_mfma_f32_16x16x32_bf16 v[106:109], v[186:189], v[194:197], v[106:109]
	v_mfma_f32_16x16x32_bf16 v[98:101], v[178:181], v[202:205], v[98:101]
	v_mfma_f32_16x16x32_bf16 v[90:93], v[186:189], v[202:205], v[90:93]
	v_mfma_f32_16x16x32_bf16 v[82:85], v[178:181], v[210:213], v[82:85]
	v_mfma_f32_16x16x32_bf16 v[74:77], v[186:189], v[210:213], v[74:77]
	v_mfma_f32_16x16x32_bf16 v[70:73], v[178:181], v[218:221], v[70:73]
	v_mfma_f32_16x16x32_bf16 v[66:69], v[186:189], v[218:221], v[66:69]
	s_setprio 0
	s_barrier
	s_add_i32 s40, s40, s3
	v_lshl_add_u64 v[164:165], s[26:27], 0, v[0:1]
	s_mov_b32 m0, s40
	ds_read_b128 v[190:193], v147 offset:16384
	ds_read_b128 v[194:197], v147 offset:17408
	ds_read_b128 v[198:201], v147 offset:18432
	ds_read_b128 v[202:205], v147 offset:19456
	ds_read_b128 v[206:209], v147 offset:20480
	ds_read_b128 v[210:213], v147 offset:21504
	ds_read_b128 v[214:217], v147 offset:22528
	ds_read_b128 v[218:221], v147 offset:23552
	global_load_lds_dwordx4 v[164:165], off
	s_add_i32 m0, s40, 0x2000
	s_add_u32 s40, s26, 0x40000
	v_lshl_add_u64 v[166:167], s[26:27], 0, v[130:131]
	s_addc_u32 s41, s27, 0
	s_add_i32 s42, s42, s3
	global_load_lds_dwordx4 v[166:167], off
	v_lshl_add_u64 v[168:169], s[40:41], 0, v[0:1]
	s_mov_b32 m0, s42
	v_lshl_add_u64 v[170:171], s[28:29], 0, v[132:133]
	global_load_lds_dwordx4 v[168:169], off
	v_lshl_add_u64 v[168:169], s[40:41], 0, v[130:131]
	s_add_i32 m0, s42, 0x2000
	s_nop 0
	global_load_lds_dwordx4 v[168:169], off
	v_lshl_add_u64 v[168:169], s[28:29], 0, v[134:135]
	s_mov_b32 m0, s8
	s_nop 0
	global_load_lds_dwordx4 v[168:169], off
	s_mov_b32 m0, s9
	s_nop 0
	global_load_lds_dwordx4 v[170:171], off
	s_waitcnt vmcnt(8)
	s_waitcnt lgkmcnt(0)
	s_barrier
; #define PG8_STAGE(bufoff, gbase, voff) do { _Pragma("unroll") for (int _i = 0; _i < 2; ++_i) \
;         __builtin_amdgcn_global_load_lds((const unsigned*)((const char*)(gbase) + (voff)[_i]), (PG8_LAS unsigned*)(lds + (bufoff) + ldsw + _i * 8192), 16, 0, 0); } while (0)
; #define PG8_LDA(dst, b, h) do { _Pragma("unroll") for (int m = 0; m < 4; ++m) _Pragma("unroll") for (int k = 0; k < 2; ++k) dst[m][k] = *(const PG8_LAS bf16x8*)(lds + PG8_SA(b, h) + aoff + m * 2048 + k * 1024); } while (0)
; #define PG8_LDB(dst, b, h) do { _Pragma("unroll") for (int n = 0; n < 2; ++n) _Pragma("unroll") for (int k = 0; k < 2; ++k) dst[n][k] = *(const PG8_LAS bf16x8*)(lds + PG8_SB(b, h) + boff + n * 2048 + k * 1024); } while (0)
; #define PG8_MMA(ai, bj, At, Bt) do { __builtin_amdgcn_s_setprio(1); _Pragma("unroll") for (int m = 0; m < 4; ++m) _Pragma("unroll") for (int n = 0; n < 2; ++n) _Pragma("unroll") for (int k = 0; k < 2; ++k) \
;         acc[ai][bj][m][n] = __builtin_amdgcn_mfma_f32_16x16x32_bf16(Bt[n][k], At[m][k], acc[ai][bj][m][n], 0, 0, 0); __builtin_amdgcn_s_setprio(0); } while (0)
; #define PG8_WAIT_V(n) asm volatile("s_waitcnt vmcnt(" #n ")" ::: "memory")
; #define PG8_WAIT_L(n) asm volatile("s_waitcnt lgkmcnt(" #n ")" ::: "memory")
; #define PG8_BAR __builtin_amdgcn_s_barrier()
; #define PG8_SCHED __builtin_amdgcn_sched_barrier(0)
; template <class Epi, class Sched, bool ALIGN_EPI = false, bool SP2 = false, bool UNIFORM_NT = false>
; __device__ __forceinline__ void gemm_phase(PG8_LAS unsigned char* lds, const Gemm g, const Sched& S, const Epi& E, int tid_in) {
;     ...
;             PG8_WAIT_V(8); PG8_WAIT_L(0); PG8_BAR; PG8_MMA(1, 0, At, B0); PG8_MMA(1, 1, At, B1); PG8_BAR; PG8_SCHED;
;             PG8_LDB(B0, 1, 0); PG8_LDB(B1, 1, 1); PG8_SCHED; PG8_LDA(At, 1, 0); PG8_STAGE(PG8_SA(0, 1), a2 + hstepA, voffA);
;             PG8_WAIT_V(8); PG8_WAIT_L(0); PG8_BAR; PG8_MMA(0, 0, At, B0); PG8_MMA(0, 1, At, B1); PG8_BAR; PG8_SCHED;
	s_setprio 1
	s_waitcnt lgkmcnt(0)
	v_mfma_f32_16x16x32_bf16 v[62:65], v[140:143], v[190:193], v[62:65]
	v_mfma_f32_16x16x32_bf16 v[58:61], v[152:155], v[190:193], v[58:61]
	v_mfma_f32_16x16x32_bf16 v[54:57], v[140:143], v[198:201], v[54:57]
	v_mfma_f32_16x16x32_bf16 v[46:49], v[152:155], v[198:201], v[46:49]
	v_mfma_f32_16x16x32_bf16 v[38:41], v[140:143], v[206:209], v[38:41]
	v_mfma_f32_16x16x32_bf16 v[30:33], v[152:155], v[206:209], v[30:33]
	v_mfma_f32_16x16x32_bf16 v[22:25], v[140:143], v[214:217], v[22:25]
	v_mfma_f32_16x16x32_bf16 v[14:17], v[152:155], v[214:217], v[14:17]
	v_mfma_f32_16x16x32_bf16 v[62:65], v[148:151], v[194:197], v[62:65]
	v_mfma_f32_16x16x32_bf16 v[58:61], v[156:159], v[194:197], v[58:61]
	v_mfma_f32_16x16x32_bf16 v[54:57], v[148:151], v[202:205], v[54:57]
	v_mfma_f32_16x16x32_bf16 v[46:49], v[156:159], v[202:205], v[46:49]
	v_mfma_f32_16x16x32_bf16 v[38:41], v[148:151], v[210:213], v[38:41]
	v_mfma_f32_16x16x32_bf16 v[30:33], v[156:159], v[210:213], v[30:33]
	v_mfma_f32_16x16x32_bf16 v[22:25], v[148:151], v[218:221], v[22:25]
	v_mfma_f32_16x16x32_bf16 v[14:17], v[156:159], v[218:221], v[14:17]
	s_setprio 0
	s_setprio 1
	v_mfma_f32_16x16x32_bf16 v[50:53], v[160:163], v[190:193], v[50:53]
	v_mfma_f32_16x16x32_bf16 v[42:45], v[182:185], v[190:193], v[42:45]
	v_mfma_f32_16x16x32_bf16 v[34:37], v[160:163], v[198:201], v[34:37]
	v_mfma_f32_16x16x32_bf16 v[26:29], v[182:185], v[198:201], v[26:29]
	v_mfma_f32_16x16x32_bf16 v[18:21], v[160:163], v[206:209], v[18:21]
	v_mfma_f32_16x16x32_bf16 v[10:13], v[182:185], v[206:209], v[10:13]
	v_mfma_f32_16x16x32_bf16 v[6:9], v[160:163], v[214:217], v[6:9]
	v_mfma_f32_16x16x32_bf16 v[2:5], v[182:185], v[214:217], v[2:5]
	v_mfma_f32_16x16x32_bf16 v[50:53], v[178:181], v[194:197], v[50:53]
	v_mfma_f32_16x16x32_bf16 v[42:45], v[186:189], v[194:197], v[42:45]
	v_mfma_f32_16x16x32_bf16 v[34:37], v[178:181], v[202:205], v[34:37]
	v_mfma_f32_16x16x32_bf16 v[26:29], v[186:189], v[202:205], v[26:29]
	v_mfma_f32_16x16x32_bf16 v[18:21], v[178:181], v[210:213], v[18:21]
	v_mfma_f32_16x16x32_bf16 v[10:13], v[186:189], v[210:213], v[10:13]
	v_mfma_f32_16x16x32_bf16 v[6:9], v[178:181], v[218:221], v[6:9]
	v_mfma_f32_16x16x32_bf16 v[2:5], v[186:189], v[218:221], v[2:5]
	s_setprio 0
	s_barrier
	s_add_i32 s40, 0, 0x18000
	s_add_i32 s41, 0, 0x1c000
	v_add_u32_e32 v156, s40, v145
	v_add_u32_e32 v172, s41, v145
	ds_read_b128 v[140:143], v156
	ds_read_b128 v[148:151], v156 offset:1024
	ds_read_b128 v[152:155], v156 offset:2048
	ds_read_b128 v[156:159], v156 offset:3072
	ds_read_b128 v[160:163], v172
	ds_read_b128 v[178:181], v172 offset:1024
	ds_read_b128 v[182:185], v172 offset:2048
	ds_read_b128 v[186:189], v172 offset:3072
	s_add_u32 s28, s28, 0x40000
	s_addc_u32 s29, s29, 0
	s_mov_b32 m0, s14
	v_lshl_add_u64 v[172:173], s[28:29], 0, v[134:135]
	ds_read_b128 v[190:193], v147 offset:32768
	ds_read_b128 v[194:197], v147 offset:33792
	ds_read_b128 v[198:201], v147 offset:34816
	ds_read_b128 v[202:205], v147 offset:35840
	ds_read_b128 v[206:209], v147 offset:36864
	ds_read_b128 v[210:213], v147 offset:37888
	ds_read_b128 v[214:217], v147 offset:38912
	ds_read_b128 v[218:221], v147 offset:39936
	global_load_lds_dwordx4 v[172:173], off
	v_lshl_add_u64 v[172:173], s[28:29], 0, v[132:133]
	s_mov_b32 m0, s15
	s_nop 0
	global_load_lds_dwordx4 v[172:173], off
	s_waitcnt vmcnt(8)
	s_waitcnt lgkmcnt(0)
	s_barrier
	s_setprio 1
	s_waitcnt lgkmcnt(0)
	v_mfma_f32_16x16x32_bf16 v[126:129], v[140:143], v[190:193], v[126:129]
	v_mfma_f32_16x16x32_bf16 v[122:125], v[152:155], v[190:193], v[122:125]
	v_mfma_f32_16x16x32_bf16 v[118:121], v[140:143], v[198:201], v[118:121]
	v_mfma_f32_16x16x32_bf16 v[110:113], v[152:155], v[198:201], v[110:113]
	v_mfma_f32_16x16x32_bf16 v[102:105], v[140:143], v[206:209], v[102:105]
	v_mfma_f32_16x16x32_bf16 v[94:97], v[152:155], v[206:209], v[94:97]
	v_mfma_f32_16x16x32_bf16 v[86:89], v[140:143], v[214:217], v[86:89]
	v_mfma_f32_16x16x32_bf16 v[78:81], v[152:155], v[214:217], v[78:81]
	v_mfma_f32_16x16x32_bf16 v[126:129], v[148:151], v[194:197], v[126:129]
	v_mfma_f32_16x16x32_bf16 v[122:125], v[156:159], v[194:197], v[122:125]
	v_mfma_f32_16x16x32_bf16 v[118:121], v[148:151], v[202:205], v[118:121]
	v_mfma_f32_16x16x32_bf16 v[110:113], v[156:159], v[202:205], v[110:113]
	v_mfma_f32_16x16x32_bf16 v[102:105], v[148:151], v[210:213], v[102:105]
	v_mfma_f32_16x16x32_bf16 v[94:97], v[156:159], v[210:213], v[94:97]
	v_mfma_f32_16x16x32_bf16 v[86:89], v[148:151], v[218:221], v[86:89]
	v_mfma_f32_16x16x32_bf16 v[78:81], v[156:159], v[218:221], v[78:81]
	s_setprio 0
	s_setprio 1
	v_mfma_f32_16x16x32_bf16 v[114:117], v[160:163], v[190:193], v[114:117]
	v_mfma_f32_16x16x32_bf16 v[106:109], v[182:185], v[190:193], v[106:109]
	v_mfma_f32_16x16x32_bf16 v[98:101], v[160:163], v[198:201], v[98:101]
	v_mfma_f32_16x16x32_bf16 v[90:93], v[182:185], v[198:201], v[90:93]
	v_mfma_f32_16x16x32_bf16 v[82:85], v[160:163], v[206:209], v[82:85]
	v_mfma_f32_16x16x32_bf16 v[74:77], v[182:185], v[206:209], v[74:77]
	v_mfma_f32_16x16x32_bf16 v[70:73], v[160:163], v[214:217], v[70:73]
	v_mfma_f32_16x16x32_bf16 v[66:69], v[182:185], v[214:217], v[66:69]
	v_mfma_f32_16x16x32_bf16 v[114:117], v[178:181], v[194:197], v[114:117]
	v_mfma_f32_16x16x32_bf16 v[106:109], v[186:189], v[194:197], v[106:109]
	v_mfma_f32_16x16x32_bf16 v[98:101], v[178:181], v[202:205], v[98:101]
	v_mfma_f32_16x16x32_bf16 v[90:93], v[186:189], v[202:205], v[90:93]
	v_mfma_f32_16x16x32_bf16 v[82:85], v[178:181], v[210:213], v[82:85]
	v_mfma_f32_16x16x32_bf16 v[74:77], v[186:189], v[210:213], v[74:77]
	v_mfma_f32_16x16x32_bf16 v[70:73], v[178:181], v[218:221], v[70:73]
	v_mfma_f32_16x16x32_bf16 v[66:69], v[186:189], v[218:221], v[66:69]
	s_setprio 0
	s_barrier
; #define PG8_STAGE(bufoff, gbase, voff) do { _Pragma("unroll") for (int _i = 0; _i < 2; ++_i) \
;         __builtin_amdgcn_global_load_lds((const unsigned*)((const char*)(gbase) + (voff)[_i]), (PG8_LAS unsigned*)(lds + (bufoff) + ldsw + _i * 8192), 16, 0, 0); } while (0)
; #define PG8_LDA(dst, b, h) do { _Pragma("unroll") for (int m = 0; m < 4; ++m) _Pragma("unroll") for (int k = 0; k < 2; ++k) dst[m][k] = *(const PG8_LAS bf16x8*)(lds + PG8_SA(b, h) + aoff + m * 2048 + k * 1024); } while (0)
; #define PG8_MMA(ai, bj, At, Bt) do { __builtin_amdgcn_s_setprio(1); _Pragma("unroll") for (int m = 0; m < 4; ++m) _Pragma("unroll") for (int n = 0; n < 2; ++n) _Pragma("unroll") for (int k = 0; k < 2; ++k) \
;         acc[ai][bj][m][n] = __builtin_amdgcn_mfma_f32_16x16x32_bf16(Bt[n][k], At[m][k], acc[ai][bj][m][n], 0, 0, 0); __builtin_amdgcn_s_setprio(0); } while (0)
; #define PG8_WAIT_V(n) asm volatile("s_waitcnt vmcnt(" #n ")" ::: "memory")
; #define PG8_WAIT_L(n) asm volatile("s_waitcnt lgkmcnt(" #n ")" ::: "memory")
; #define PG8_BAR __builtin_amdgcn_s_barrier()
; #define PG8_SCHED __builtin_amdgcn_sched_barrier(0)
; template <class Epi, class Sched, bool ALIGN_EPI = false, bool SP2 = false, bool UNIFORM_NT = false>
; __device__ __forceinline__ void gemm_phase(PG8_LAS unsigned char* lds, const Gemm g, const Sched& S, const Epi& E, int tid_in) {
;     ...
;         for (int t = 0; t < nt; t += 2) {
;             const bool last = (t == nt - 2);
;             const char* a1 = cA + (size_t)(t + 1) * kstep;
;             const char* a2 = last ? nA : cA + (size_t)(t + 2) * kstep; const char* b2 = last ? nB : cB + (size_t)(t + 2) * kstep;
;     ...
;             PG8_LDA(At, 1, 1); PG8_STAGE(PG8_SB(1, 0), b3, voffB); PG8_STAGE(PG8_SB(1, 1), b3 + hstepB, voffB); PG8_STAGE(PG8_SA(1, 0), a3, voffA);
;             PG8_WAIT_V(8); PG8_WAIT_L(0); PG8_BAR; PG8_MMA(1, 0, At, B0); PG8_MMA(1, 1, At, B1); PG8_BAR; PG8_SCHED;
	s_add_i32 s28, s40, s3
	v_lshl_add_u64 v[164:165], v[164:165], 0, s[82:83]
	s_mov_b32 m0, s28
	ds_read_b128 v[190:193], v147 offset:49152
	ds_read_b128 v[194:197], v147 offset:50176
	ds_read_b128 v[198:201], v147 offset:51200
	ds_read_b128 v[202:205], v147 offset:52224
	ds_read_b128 v[206:209], v147 offset:53248
	ds_read_b128 v[210:213], v147 offset:54272
	ds_read_b128 v[214:217], v147 offset:55296
	ds_read_b128 v[218:221], v147 offset:56320
	global_load_lds_dwordx4 v[164:165], off
	s_add_i32 m0, s28, 0x2000
	s_add_u32 s26, s26, 0x40080
	v_lshl_add_u64 v[164:165], v[166:167], 0, s[82:83]
	s_addc_u32 s27, s27, 0
	s_add_i32 s28, s41, s3
	global_load_lds_dwordx4 v[164:165], off
	v_lshl_add_u64 v[164:165], s[26:27], 0, v[0:1]
	s_mov_b32 m0, s28
	s_nop 0
	global_load_lds_dwordx4 v[164:165], off
	v_lshl_add_u64 v[164:165], s[26:27], 0, v[130:131]
	s_add_i32 m0, s28, 0x2000
	s_nop 0
	global_load_lds_dwordx4 v[164:165], off
	v_lshl_add_u64 v[164:165], v[168:169], 0, s[82:83]
	s_mov_b32 m0, s30
	s_nop 0
	global_load_lds_dwordx4 v[164:165], off
	v_lshl_add_u64 v[164:165], v[170:171], 0, s[82:83]
	s_mov_b32 m0, s31
	s_nop 0
	global_load_lds_dwordx4 v[164:165], off
	s_waitcnt vmcnt(8)
	s_waitcnt lgkmcnt(0)
	s_barrier
	s_setprio 1
	s_waitcnt lgkmcnt(0)
	v_mfma_f32_16x16x32_bf16 v[62:65], v[140:143], v[190:193], v[62:65]
	v_mfma_f32_16x16x32_bf16 v[58:61], v[152:155], v[190:193], v[58:61]
	v_mfma_f32_16x16x32_bf16 v[54:57], v[140:143], v[198:201], v[54:57]
	v_mfma_f32_16x16x32_bf16 v[46:49], v[152:155], v[198:201], v[46:49]
	v_mfma_f32_16x16x32_bf16 v[38:41], v[140:143], v[206:209], v[38:41]
	v_mfma_f32_16x16x32_bf16 v[30:33], v[152:155], v[206:209], v[30:33]
	v_mfma_f32_16x16x32_bf16 v[22:25], v[140:143], v[214:217], v[22:25]
	v_mfma_f32_16x16x32_bf16 v[14:17], v[152:155], v[214:217], v[14:17]
	v_mfma_f32_16x16x32_bf16 v[62:65], v[148:151], v[194:197], v[62:65]
	v_mfma_f32_16x16x32_bf16 v[58:61], v[156:159], v[194:197], v[58:61]
	v_mfma_f32_16x16x32_bf16 v[54:57], v[148:151], v[202:205], v[54:57]
	v_mfma_f32_16x16x32_bf16 v[46:49], v[156:159], v[202:205], v[46:49]
	v_mfma_f32_16x16x32_bf16 v[38:41], v[148:151], v[210:213], v[38:41]
	v_mfma_f32_16x16x32_bf16 v[30:33], v[156:159], v[210:213], v[30:33]
	v_mfma_f32_16x16x32_bf16 v[22:25], v[148:151], v[218:221], v[22:25]
	v_mfma_f32_16x16x32_bf16 v[14:17], v[156:159], v[218:221], v[14:17]
	s_setprio 0
	s_setprio 1
	v_mfma_f32_16x16x32_bf16 v[50:53], v[160:163], v[190:193], v[50:53]
	v_mfma_f32_16x16x32_bf16 v[42:45], v[182:185], v[190:193], v[42:45]
	v_mfma_f32_16x16x32_bf16 v[34:37], v[160:163], v[198:201], v[34:37]
	v_mfma_f32_16x16x32_bf16 v[26:29], v[182:185], v[198:201], v[26:29]
	v_mfma_f32_16x16x32_bf16 v[18:21], v[160:163], v[206:209], v[18:21]
	v_mfma_f32_16x16x32_bf16 v[10:13], v[182:185], v[206:209], v[10:13]
	v_mfma_f32_16x16x32_bf16 v[6:9], v[160:163], v[214:217], v[6:9]
	v_mfma_f32_16x16x32_bf16 v[2:5], v[182:185], v[214:217], v[2:5]
	v_mfma_f32_16x16x32_bf16 v[50:53], v[178:181], v[194:197], v[50:53]
	v_mfma_f32_16x16x32_bf16 v[42:45], v[186:189], v[194:197], v[42:45]
	s_add_i32 s37, s37, 2
	v_mfma_f32_16x16x32_bf16 v[34:37], v[178:181], v[202:205], v[34:37]
	s_add_u32 s24, s24, 0x100
	v_mfma_f32_16x16x32_bf16 v[26:29], v[186:189], v[202:205], v[26:29]
	s_addc_u32 s25, s25, 0
	v_mfma_f32_16x16x32_bf16 v[18:21], v[178:181], v[210:213], v[18:21]
	s_add_u32 s35, s35, 0x100
	v_mfma_f32_16x16x32_bf16 v[10:13], v[186:189], v[210:213], v[10:13]
	s_addc_u32 s36, s36, 0
	v_mfma_f32_16x16x32_bf16 v[6:9], v[178:181], v[218:221], v[6:9]
	s_cmp_gt_u32 s37, 13
	v_mfma_f32_16x16x32_bf16 v[2:5], v[186:189], v[218:221], v[2:5]
	s_setprio 0
	s_barrier
	s_cbranch_scc0 .LBB0_833
	s_and_b64 vcc, exec, s[4:5]
	s_cbranch_vccz .LBB0_836
	s_barrier
